# w_in and second gate/up GEMM: per-row scale loads issued before the K-loop; epilogues no longer wait vmcnt(0) (which drained the next unit's prefetched tiles)
# baseline (speedup 1.0000x reference)
; #define PG8_STAGE(bufoff, gbase, voff) do { _Pragma("unroll") for (int _i = 0; _i < 2; ++_i) \
;         __builtin_amdgcn_global_load_lds((const unsigned*)((const char*)(gbase) + (voff)[_i]), (PG8_LAS unsigned*)(lds + (bufoff) + ldsw + _i * 8192), 16, 0, 0); } while (0)
; #define PG8_WAIT_V(n) asm volatile("s_waitcnt vmcnt(" #n ")" ::: "memory")
;     __device__ __forceinline__ void operator()(const f32x4 (&acc)[2][2][4][2], const Unit& u, int wr, int wc, int fr, int fq) const {
;     ...
;                     const float rsc = rs ? rs[row0 + ai * HALF + m * 16] : 1.0f;
; template <class Epi, class Sched, bool ALIGN_EPI = false, bool SP2 = false>
; __device__ __forceinline__ void gemm_phase(PG8_LAS unsigned char* lds, const Gemm g, const Sched& S, const Epi& E) {
;     ...
;     f32x4 acc[2][2][4][2];
; #pragma unroll
;     for (int a = 0; a < 2; ++a)
; #pragma unroll
;         for (int b = 0; b < 2; ++b)
; #pragma unroll
;             for (int m = 0; m < 4; ++m)
; #pragma unroll
;                 for (int n = 0; n < 2; ++n) acc[a][b][m][n] = (f32x4){0.f, 0.f, 0.f, 0.f};
;     bf16x8 At[4][2], B0[2][2], B1[2][2];
;     const char* cA = (const char*)g.A + (size_t)cur.pm * tstep; const char* cB = (const char*)g.Bt + (size_t)cur.pn * tstep;
;     S.a_ready(cur);
;     if constexpr (SP2) {
;         PG8_STAGE(PG8_SB(0, 0), cB, voffB); PG8_STAGE(PG8_SB(0, 1), cB + hstep, voffB); PG8_STAGE(PG8_SA(0, 0), cA, voffA); PG8_STAGE(PG8_SA(0, 1), cA + hstep, voffA);
;         if (wr == 1) PG8_BAR;
;         PG8_WAIT_V(2); PG8_BAR;
;         PG8_STAGE(PG8_SB(1, 0), cB + kstep, voffB); PG8_STAGE(PG8_SA(1, 0), cA + kstep, voffA); PG8_STAGE(PG8_SB(1, 1), cB + hstep + kstep, voffB);
;         PG8_WAIT_V(6); PG8_BAR;
;     } else {
;         PG8_STAGE(PG8_SB(0, 0), cB, voffB); PG8_STAGE(PG8_SA(0, 0), cA, voffA); PG8_STAGE(PG8_SB(0, 1), cB + hstep, voffB); PG8_STAGE(PG8_SA(0, 1), cA + hstep, voffA);
;         if (wr == 1) PG8_BAR;
;         PG8_WAIT_V(4); PG8_BAR;
;         PG8_STAGE(PG8_SB(1, 0), cB + kstep, voffB); PG8_STAGE(PG8_SA(1, 0), cA + kstep, voffA); PG8_STAGE(PG8_SB(1, 1), cB + hstep + kstep, voffB);
;         PG8_WAIT_V(6); PG8_BAR;
;     }
;     for (;;) {
;         const bool has_next = S.next(ui + 1, nxt);
;         const char* nA = has_next ? (const char*)g.A + (size_t)nxt.pm * tstep : cA; const char* nB = has_next ? (const char*)g.Bt + (size_t)nxt.pn * tstep : cB;
.LBB0_524:
	s_ashr_i32 s23, s22, 31
	s_lshl_b64 s[24:25], s[22:23], 19
	s_add_u32 s24, s62, s24
	s_addc_u32 s25, s63, s25
	s_and_b64 s[26:27], s[0:1], exec
	s_cselect_b32 s3, s25, s31
	s_cselect_b32 s23, s24, s30
	s_ashr_i32 s21, s20, 31
	s_lshl_b64 s[26:27], s[20:21], 19
	s_add_u32 s26, s6, s26
	s_addc_u32 s27, s7, s27
	s_and_b64 s[36:37], s[0:1], exec
	s_cselect_b32 s21, s27, s35
	s_cselect_b32 s50, s26, s34
	s_add_u32 s30, s30, 0x40080
	s_addc_u32 s31, s31, 0
	s_add_u32 s51, s34, 0x100
	v_mov_b32_e32 v0, 0
	s_addc_u32 s52, s35, 0
	s_mov_b32 s53, -2
	v_mov_b32_e32 v1, v0
	v_mov_b32_e32 v2, v0
	v_mov_b32_e32 v3, v0
	v_mov_b32_e32 v4, v0
	v_mov_b32_e32 v5, v0
	v_mov_b32_e32 v6, v0
	v_mov_b32_e32 v7, v0
	v_mov_b32_e32 v8, v0
	v_mov_b32_e32 v9, v0
	v_mov_b32_e32 v10, v0
	v_mov_b32_e32 v11, v0
	v_mov_b32_e32 v12, v0
	v_mov_b32_e32 v13, v0
	v_mov_b32_e32 v14, v0
	v_mov_b32_e32 v15, v0
	v_mov_b32_e32 v16, v0
	v_mov_b32_e32 v17, v0
	v_mov_b32_e32 v18, v0
	v_mov_b32_e32 v19, v0
	v_mov_b32_e32 v20, v0
	v_mov_b32_e32 v21, v0
	v_mov_b32_e32 v22, v0
	v_mov_b32_e32 v23, v0
	v_mov_b32_e32 v24, v0
	v_mov_b32_e32 v25, v0
	v_mov_b32_e32 v26, v0
	v_mov_b32_e32 v27, v0
	v_mov_b32_e32 v28, v0
	v_mov_b32_e32 v29, v0
	v_mov_b32_e32 v30, v0
	v_mov_b32_e32 v31, v0
	v_mov_b32_e32 v60, v0
	v_mov_b32_e32 v61, v0
	v_mov_b32_e32 v62, v0
	v_mov_b32_e32 v63, v0
	v_mov_b32_e32 v68, v0
	v_mov_b32_e32 v69, v0
	v_mov_b32_e32 v70, v0
	v_mov_b32_e32 v71, v0
	v_mov_b32_e32 v72, v0
	v_mov_b32_e32 v73, v0
	v_mov_b32_e32 v74, v0
	v_mov_b32_e32 v75, v0
	v_mov_b32_e32 v76, v0
	v_mov_b32_e32 v77, v0
	v_mov_b32_e32 v78, v0
	v_mov_b32_e32 v79, v0
	v_mov_b32_e32 v80, v0
	v_mov_b32_e32 v81, v0
	v_mov_b32_e32 v82, v0
	v_mov_b32_e32 v83, v0
	v_mov_b32_e32 v84, v0
	v_mov_b32_e32 v85, v0
	v_mov_b32_e32 v86, v0
	v_mov_b32_e32 v87, v0
	v_mov_b32_e32 v88, v0
	v_mov_b32_e32 v89, v0
	v_mov_b32_e32 v90, v0
	v_mov_b32_e32 v91, v0
	v_mov_b32_e32 v92, v0
	v_mov_b32_e32 v93, v0
	v_mov_b32_e32 v94, v0
	v_mov_b32_e32 v95, v0
	v_mov_b32_e32 v32, v0
	v_mov_b32_e32 v33, v0
	v_mov_b32_e32 v34, v0
	v_mov_b32_e32 v35, v0
	v_mov_b32_e32 v36, v0
	v_mov_b32_e32 v37, v0
	v_mov_b32_e32 v38, v0
	v_mov_b32_e32 v39, v0
	v_mov_b32_e32 v40, v0
	v_mov_b32_e32 v41, v0
	v_mov_b32_e32 v42, v0
	v_mov_b32_e32 v43, v0
	v_mov_b32_e32 v44, v0
	v_mov_b32_e32 v45, v0
	v_mov_b32_e32 v46, v0
	v_mov_b32_e32 v47, v0
	v_mov_b32_e32 v48, v0
	v_mov_b32_e32 v49, v0
	v_mov_b32_e32 v50, v0
	v_mov_b32_e32 v51, v0
	v_mov_b32_e32 v52, v0
	v_mov_b32_e32 v53, v0
	v_mov_b32_e32 v54, v0
	v_mov_b32_e32 v55, v0
	v_mov_b32_e32 v56, v0
	v_mov_b32_e32 v57, v0
	v_mov_b32_e32 v58, v0
	v_mov_b32_e32 v59, v0
	v_mov_b32_e32 v64, v0
	v_mov_b32_e32 v65, v0
	v_mov_b32_e32 v66, v0
	v_mov_b32_e32 v67, v0
	v_mov_b32_e32 v96, v0
	v_mov_b32_e32 v97, v0
	v_mov_b32_e32 v98, v0
	v_mov_b32_e32 v99, v0
	v_mov_b32_e32 v100, v0
	v_mov_b32_e32 v101, v0
	v_mov_b32_e32 v102, v0
	v_mov_b32_e32 v103, v0
	v_mov_b32_e32 v104, v0
	v_mov_b32_e32 v105, v0
	v_mov_b32_e32 v106, v0
	v_mov_b32_e32 v107, v0
	v_mov_b32_e32 v108, v0
	v_mov_b32_e32 v109, v0
	v_mov_b32_e32 v110, v0
	v_mov_b32_e32 v111, v0
	v_mov_b32_e32 v112, v0
	v_mov_b32_e32 v113, v0
	v_mov_b32_e32 v114, v0
	v_mov_b32_e32 v115, v0
	v_mov_b32_e32 v116, v0
	v_mov_b32_e32 v117, v0
	v_mov_b32_e32 v118, v0
	v_mov_b32_e32 v119, v0
	v_mov_b32_e32 v120, v0
	v_mov_b32_e32 v121, v0
	v_mov_b32_e32 v122, v0
	v_mov_b32_e32 v123, v0
	v_mov_b32_e32 v124, v0
	v_mov_b32_e32 v125, v0
	v_mov_b32_e32 v126, v0
	v_mov_b32_e32 v127, v0
	v_lshl_add_u32 v144, s2, 8, v153
	v_ashrrev_i32_e32 v145, 31, v144
	v_lshl_add_u64 v[146:147], v[144:145], 2, s[4:5]
	global_load_dword v230, v[146:147], off
	global_load_dword v232, v[146:147], off offset:64
	global_load_dword v234, v[146:147], off offset:128
	global_load_dword v236, v[146:147], off offset:192
	global_load_dword v238, v[146:147], off offset:512
	global_load_dword v240, v[146:147], off offset:576
	global_load_dword v242, v[146:147], off offset:640
	global_load_dword v244, v[146:147], off offset:704

; __device__ __forceinline__ unsigned cvt_pk_bf16(float lo, float hi) { unsigned r; asm volatile("v_cvt_pk_bf16_f32 %0, %1, %2" : "=v"(r) : "v"(lo), "v"(hi)); return r; }
;     __device__ __forceinline__ void operator()(const f32x4 (&acc)[2][2][4][2], const Unit& u, int wr, int wc, int fr, int fq) const {
;     ...
;         for (int bj = 0; bj < 2; ++bj) {
;             const int c = u.pn * BM + bj * HALF + wc * 32 + 8 * fq;
;             bf16_t* base; size_t ld;
;             if (MODE == 1) { if (c < 1024) { base = O + c; ld = 1024; } else { base = O2 + (c - 1024); ld = 1536; } }
;             else if (MODE == 2) { base = O + (c >> 6) * 96 + (c & 63); ld = (size_t)ldc; }
;             else { base = O + c; ld = (size_t)ldc; }
; #pragma unroll
;             for (int ai = 0; ai < 2; ++ai)
; #pragma unroll
;                 for (int m = 0; m < 4; ++m) {
;                     const float rsc = rs ? rs[row0 + ai * HALF + m * 16] : 1.0f;
;                     const f32x4 v0 = acc[ai][bj][m][0] * rsc, v1 = acc[ai][bj][m][1] * rsc;
;                     u32x4 w; w.x = cvt_pk_bf16(v0[0], v0[1]); w.y = cvt_pk_bf16(v0[2], v0[3]); w.z = cvt_pk_bf16(v1[0], v1[1]); w.w = cvt_pk_bf16(v1[2], v1[3]);
;                     *(u32x4*)(base + (size_t)(row0 + ai * HALF + m * 16) * ld) = w;
;                 }
.LBB0_528:
	v_lshl_add_u32 v144, s2, 8, v153
	v_ashrrev_i32_e32 v145, 31, v144
	v_cndmask_b32_e64 v146, 0, 1, s[12:13]
	v_mov_b32_e32 v152, 1.0
	v_cmp_ne_u32_e64 s[2:3], 1, v146
	s_andn2_b64 vcc, exec, s[12:13]
	v_lshl_add_u64 v[146:147], v[144:145], 2, s[4:5]
	v_mov_b32_e32 v154, 1.0
	s_cbranch_vccnz .LBB0_530
.LBB0_530:
	v_lshl_or_b32 v148, s28, 8, v156
	v_readlane_b32 s30, v253, 47
	v_ashrrev_i32_e32 v149, 31, v148
	v_readlane_b32 s31, v253, 48
	v_cmp_gt_i32_e32 vcc, s49, v148
	s_nop 1
	v_pk_mul_f32 v[124:125], v[124:125], v[230:231] op_sel_hi:[1,0]
	v_lshl_add_u64 v[150:151], v[148:149], 1, s[30:31]
	v_readlane_b32 s30, v253, 51
	v_mov_b32_e32 v149, v131
	v_readlane_b32 s31, v253, 52
	v_cndmask_b32_e32 v145, v160, v161, vcc
	v_pk_mul_f32 v[126:127], v[126:127], v[230:231] op_sel_hi:[1,0]
	v_lshl_add_u64 v[162:163], v[148:149], 1, s[30:31]
	v_lshl_add_u64 v[162:163], v[162:163], 0, s[18:19]
	v_cndmask_b32_e32 v151, v163, v151, vcc
	v_cndmask_b32_e32 v150, v162, v150, vcc
	v_pk_mul_f32 v[162:163], v[122:123], v[230:231] op_sel_hi:[1,0]
	v_pk_mul_f32 v[122:123], v[120:121], v[230:231] op_sel_hi:[1,0]
	v_cvt_pk_bf16_f32 v120, v124, v125
	v_mad_i64_i32 v[124:125], s[30:31], v145, v144, 0
	v_lshl_add_u64 v[124:125], v[124:125], 1, v[150:151]
	v_cvt_pk_bf16_f32 v121, v126, v127
	v_cvt_pk_bf16_f32 v122, v122, v123
	v_cvt_pk_bf16_f32 v123, v162, v163
	global_store_dwordx4 v[124:125], v[120:123], off
	s_and_b64 vcc, exec, s[2:3]
	s_nop 0
	v_or_b32_e32 v120, 16, v144
	v_ashrrev_i32_e32 v121, 31, v120
	v_lshl_add_u64 v[122:123], v[120:121], 2, s[4:5]
	s_cbranch_vccnz .LBB0_532
.LBB0_532:
	s_nop 1
	v_pk_mul_f32 v[116:117], v[116:117], v[232:233] op_sel_hi:[1,0]
	v_pk_mul_f32 v[124:125], v[114:115], v[232:233] op_sel_hi:[1,0]
	v_pk_mul_f32 v[114:115], v[112:113], v[232:233] op_sel_hi:[1,0]
	v_cvt_pk_bf16_f32 v112, v116, v117
	v_mad_i64_i32 v[116:117], s[30:31], v145, v120, 0
	v_lshl_add_u64 v[116:117], v[116:117], 1, v[150:151]
	v_pk_mul_f32 v[118:119], v[118:119], v[232:233] op_sel_hi:[1,0]
	s_and_b64 vcc, exec, s[2:3]
	v_cvt_pk_bf16_f32 v113, v118, v119
	v_cvt_pk_bf16_f32 v114, v114, v115
	v_cvt_pk_bf16_f32 v115, v124, v125
	global_store_dwordx4 v[116:117], v[112:115], off
	v_mov_b32_e32 v116, 1.0
	v_mov_b32_e32 v118, 1.0
	v_or_b32_e32 v112, 32, v144
	v_ashrrev_i32_e32 v113, 31, v112
	v_lshl_add_u64 v[114:115], v[112:113], 2, s[4:5]
	s_cbranch_vccnz .LBB0_534
.LBB0_534:
	s_nop 1
	v_pk_mul_f32 v[108:109], v[108:109], v[234:235] op_sel_hi:[1,0]
	v_pk_mul_f32 v[124:125], v[106:107], v[234:235] op_sel_hi:[1,0]
	v_pk_mul_f32 v[106:107], v[104:105], v[234:235] op_sel_hi:[1,0]
	v_cvt_pk_bf16_f32 v104, v108, v109
	v_mad_i64_i32 v[108:109], s[30:31], v145, v112, 0
	v_lshl_add_u64 v[108:109], v[108:109], 1, v[150:151]
	v_pk_mul_f32 v[110:111], v[110:111], v[234:235] op_sel_hi:[1,0]
	s_and_b64 vcc, exec, s[2:3]
	v_cvt_pk_bf16_f32 v105, v110, v111
	v_cvt_pk_bf16_f32 v106, v106, v107
	v_cvt_pk_bf16_f32 v107, v124, v125
	global_store_dwordx4 v[108:109], v[104:107], off
	s_nop 1
	v_or_b32_e32 v104, 48, v144
	v_ashrrev_i32_e32 v105, 31, v104
	v_lshl_add_u64 v[106:107], v[104:105], 2, s[4:5]
	s_cbranch_vccnz .LBB0_536
.LBB0_536:
	s_nop 1
	v_pk_mul_f32 v[100:101], v[100:101], v[236:237] op_sel_hi:[1,0]
	v_pk_mul_f32 v[108:109], v[98:99], v[236:237] op_sel_hi:[1,0]
	v_pk_mul_f32 v[98:99], v[96:97], v[236:237] op_sel_hi:[1,0]
	v_cvt_pk_bf16_f32 v96, v100, v101
	v_mad_i64_i32 v[100:101], s[30:31], v145, v104, 0
	v_lshl_add_u64 v[100:101], v[100:101], 1, v[150:151]
	v_pk_mul_f32 v[102:103], v[102:103], v[236:237] op_sel_hi:[1,0]
	s_and_b64 vcc, exec, s[2:3]
	v_cvt_pk_bf16_f32 v97, v102, v103
	v_cvt_pk_bf16_f32 v98, v98, v99
	v_cvt_pk_bf16_f32 v99, v108, v109
	global_store_dwordx4 v[100:101], v[96:99], off
	v_mov_b32_e32 v100, 1.0
	v_mov_b32_e32 v102, 1.0
	v_add_u32_e32 v96, 0x80, v144
	v_ashrrev_i32_e32 v97, 31, v96
	v_lshl_add_u64 v[98:99], v[96:97], 2, s[4:5]
	s_cbranch_vccnz .LBB0_538
.LBB0_538:
	s_nop 1
	v_pk_mul_f32 v[92:93], v[92:93], v[238:239] op_sel_hi:[1,0]
	v_pk_mul_f32 v[108:109], v[90:91], v[238:239] op_sel_hi:[1,0]
	v_pk_mul_f32 v[90:91], v[88:89], v[238:239] op_sel_hi:[1,0]
	v_cvt_pk_bf16_f32 v88, v92, v93
	v_mad_i64_i32 v[92:93], s[30:31], v145, v96, 0
	v_lshl_add_u64 v[92:93], v[92:93], 1, v[150:151]
	v_pk_mul_f32 v[94:95], v[94:95], v[238:239] op_sel_hi:[1,0]
	s_and_b64 vcc, exec, s[2:3]
	v_cvt_pk_bf16_f32 v89, v94, v95
	v_cvt_pk_bf16_f32 v90, v90, v91
	v_cvt_pk_bf16_f32 v91, v108, v109
	global_store_dwordx4 v[92:93], v[88:91], off
	s_nop 1
	v_add_u32_e32 v88, 0x90, v144
	v_ashrrev_i32_e32 v89, 31, v88
	v_lshl_add_u64 v[90:91], v[88:89], 2, s[4:5]
	s_cbranch_vccnz .LBB0_540
.LBB0_540:
	s_nop 1
	v_pk_mul_f32 v[84:85], v[84:85], v[240:241] op_sel_hi:[1,0]
	v_pk_mul_f32 v[92:93], v[82:83], v[240:241] op_sel_hi:[1,0]
	v_pk_mul_f32 v[82:83], v[80:81], v[240:241] op_sel_hi:[1,0]
	v_cvt_pk_bf16_f32 v80, v84, v85
	v_mad_i64_i32 v[84:85], s[30:31], v145, v88, 0
	v_lshl_add_u64 v[84:85], v[84:85], 1, v[150:151]
	v_pk_mul_f32 v[86:87], v[86:87], v[240:241] op_sel_hi:[1,0]
	s_and_b64 vcc, exec, s[2:3]
	v_cvt_pk_bf16_f32 v81, v86, v87
	v_cvt_pk_bf16_f32 v82, v82, v83
	v_cvt_pk_bf16_f32 v83, v92, v93
	global_store_dwordx4 v[84:85], v[80:83], off
	v_mov_b32_e32 v84, 1.0
	v_mov_b32_e32 v86, 1.0
	v_add_u32_e32 v80, 0xa0, v144
	v_ashrrev_i32_e32 v81, 31, v80
	v_lshl_add_u64 v[82:83], v[80:81], 2, s[4:5]
	s_cbranch_vccnz .LBB0_542
; __device__ __forceinline__ unsigned cvt_pk_bf16(float lo, float hi) { unsigned r; asm volatile("v_cvt_pk_bf16_f32 %0, %1, %2" : "=v"(r) : "v"(lo), "v"(hi)); return r; }
; #define PG8_BAR __builtin_amdgcn_s_barrier()
;     __device__ __forceinline__ void operator()(const f32x4 (&acc)[2][2][4][2], const Unit& u, int wr, int wc, int fr, int fq) const {
;     ...
;         for (int bj = 0; bj < 2; ++bj) {
;             const int c = u.pn * BM + bj * HALF + wc * 32 + 8 * fq;
;             bf16_t* base; size_t ld;
;             if (MODE == 1) { if (c < 1024) { base = O + c; ld = 1024; } else { base = O2 + (c - 1024); ld = 1536; } }
;             else if (MODE == 2) { base = O + (c >> 6) * 96 + (c & 63); ld = (size_t)ldc; }
;             else { base = O + c; ld = (size_t)ldc; }
; #pragma unroll
;             for (int ai = 0; ai < 2; ++ai)
; #pragma unroll
;                 for (int m = 0; m < 4; ++m) {
;                     const float rsc = rs ? rs[row0 + ai * HALF + m * 16] : 1.0f;
;                     const f32x4 v0 = acc[ai][bj][m][0] * rsc, v1 = acc[ai][bj][m][1] * rsc;
;                     u32x4 w; w.x = cvt_pk_bf16(v0[0], v0[1]); w.y = cvt_pk_bf16(v0[2], v0[3]); w.z = cvt_pk_bf16(v1[0], v1[1]); w.w = cvt_pk_bf16(v1[2], v1[3]);
;                     *(u32x4*)(base + (size_t)(row0 + ai * HALF + m * 16) * ld) = w;
;                 }
; template <class Epi, class Sched, bool ALIGN_EPI = false, bool SP2 = false>
; __device__ __forceinline__ void gemm_phase(PG8_LAS unsigned char* lds, const Gemm g, const Sched& S, const Epi& E) {
;     ...
;         if (!has_next) break;
; #pragma unroll
;         for (int a = 0; a < 2; ++a)
; #pragma unroll
;             for (int b = 0; b < 2; ++b)
; #pragma unroll
;                 for (int m = 0; m < 4; ++m)
; #pragma unroll
;                     for (int n = 0; n < 2; ++n) acc[a][b][m][n] = (f32x4){0.f, 0.f, 0.f, 0.f};
;         cur = nxt; cA = nA; cB = nB; ++ui;
;         if constexpr (ALIGN_EPI) { if (wr == 1) PG8_BAR; }
.LBB0_542:
	s_nop 1
	v_pk_mul_f32 v[76:77], v[76:77], v[242:243] op_sel_hi:[1,0]
	v_pk_mul_f32 v[92:93], v[74:75], v[242:243] op_sel_hi:[1,0]
	v_pk_mul_f32 v[74:75], v[72:73], v[242:243] op_sel_hi:[1,0]
	v_cvt_pk_bf16_f32 v72, v76, v77
	v_mad_i64_i32 v[76:77], s[30:31], v145, v80, 0
	v_lshl_add_u64 v[76:77], v[76:77], 1, v[150:151]
	v_pk_mul_f32 v[78:79], v[78:79], v[242:243] op_sel_hi:[1,0]
	s_and_b64 vcc, exec, s[2:3]
	v_cvt_pk_bf16_f32 v73, v78, v79
	v_cvt_pk_bf16_f32 v74, v74, v75
	v_cvt_pk_bf16_f32 v75, v92, v93
	global_store_dwordx4 v[76:77], v[72:75], off
	s_nop 1
	v_add_u32_e32 v72, 0xb0, v144
	v_ashrrev_i32_e32 v73, 31, v72
	v_lshl_add_u64 v[74:75], v[72:73], 2, s[4:5]
	s_cbranch_vccnz .LBB0_544
.LBB0_544:
	s_nop 1
	v_pk_mul_f32 v[68:69], v[68:69], v[244:245] op_sel_hi:[1,0]
	v_pk_mul_f32 v[76:77], v[62:63], v[244:245] op_sel_hi:[1,0]
	v_pk_mul_f32 v[62:63], v[60:61], v[244:245] op_sel_hi:[1,0]
	v_cvt_pk_bf16_f32 v60, v68, v69
	v_mad_i64_i32 v[68:69], s[30:31], v145, v72, 0
	v_pk_mul_f32 v[70:71], v[70:71], v[244:245] op_sel_hi:[1,0]
	v_lshl_add_u64 v[68:69], v[68:69], 1, v[150:151]
	v_cvt_pk_bf16_f32 v61, v70, v71
	v_cvt_pk_bf16_f32 v62, v62, v63
	v_cvt_pk_bf16_f32 v63, v76, v77
	global_store_dwordx4 v[68:69], v[60:63], off
	s_and_b64 vcc, exec, s[2:3]
	v_mov_b32_e32 v68, 1.0
	v_mov_b32_e32 v62, 1.0
	s_cbranch_vccnz .LBB0_546
.LBB0_546:
	v_or_b32_e32 v60, 0x80, v148
	v_readlane_b32 s30, v253, 47
	v_ashrrev_i32_e32 v61, 31, v60
	v_readlane_b32 s31, v253, 48
	v_cmp_gt_i32_e32 vcc, s49, v60
	s_nop 1
	v_pk_mul_f32 v[64:65], v[64:65], v[230:231] op_sel_hi:[1,0]
	v_lshl_add_u64 v[70:71], v[60:61], 1, s[30:31]
	v_readlane_b32 s30, v253, 51
	v_mov_b32_e32 v61, v131
	v_readlane_b32 s31, v253, 52
	v_cndmask_b32_e32 v63, v160, v161, vcc
	v_pk_mul_f32 v[66:67], v[66:67], v[230:231] op_sel_hi:[1,0]
	v_lshl_add_u64 v[76:77], v[60:61], 1, s[30:31]
	v_lshl_add_u64 v[76:77], v[76:77], 0, s[18:19]
	v_cndmask_b32_e32 v61, v77, v71, vcc
	v_cndmask_b32_e32 v60, v76, v70, vcc
	v_pk_mul_f32 v[70:71], v[58:59], v[230:231] op_sel_hi:[1,0]
	v_pk_mul_f32 v[58:59], v[56:57], v[230:231] op_sel_hi:[1,0]
	v_cvt_pk_bf16_f32 v56, v64, v65
	v_mad_i64_i32 v[64:65], s[30:31], v63, v144, 0
	v_lshl_add_u64 v[64:65], v[64:65], 1, v[60:61]
	s_and_b64 vcc, exec, s[2:3]
	v_cvt_pk_bf16_f32 v57, v66, v67
	v_cvt_pk_bf16_f32 v58, v58, v59
	v_cvt_pk_bf16_f32 v59, v70, v71
	global_store_dwordx4 v[64:65], v[56:59], off
	s_cbranch_vccnz .LBB0_548
.LBB0_548:
	s_nop 1
	v_pk_mul_f32 v[52:53], v[52:53], v[232:233] op_sel_hi:[1,0]
	v_pk_mul_f32 v[56:57], v[50:51], v[232:233] op_sel_hi:[1,0]
	v_pk_mul_f32 v[50:51], v[48:49], v[232:233] op_sel_hi:[1,0]
	v_cvt_pk_bf16_f32 v48, v52, v53
	v_mad_i64_i32 v[52:53], s[30:31], v63, v120, 0
	v_pk_mul_f32 v[54:55], v[54:55], v[232:233] op_sel_hi:[1,0]
	v_lshl_add_u64 v[52:53], v[52:53], 1, v[60:61]
	v_cvt_pk_bf16_f32 v49, v54, v55
	v_cvt_pk_bf16_f32 v50, v50, v51
	v_cvt_pk_bf16_f32 v51, v56, v57
	global_store_dwordx4 v[52:53], v[48:51], off
	s_and_b64 vcc, exec, s[2:3]
	s_nop 0
	v_mov_b32_e32 v48, 1.0
	v_mov_b32_e32 v50, 1.0
	s_cbranch_vccnz .LBB0_550
.LBB0_550:
	s_nop 1
	v_pk_mul_f32 v[44:45], v[44:45], v[234:235] op_sel_hi:[1,0]
	v_pk_mul_f32 v[52:53], v[42:43], v[234:235] op_sel_hi:[1,0]
	v_pk_mul_f32 v[42:43], v[40:41], v[234:235] op_sel_hi:[1,0]
	v_cvt_pk_bf16_f32 v40, v44, v45
	v_mad_i64_i32 v[44:45], s[30:31], v63, v112, 0
	v_lshl_add_u64 v[44:45], v[44:45], 1, v[60:61]
	s_and_b64 vcc, exec, s[2:3]
	v_pk_mul_f32 v[46:47], v[46:47], v[234:235] op_sel_hi:[1,0]
	s_nop 0
	v_cvt_pk_bf16_f32 v41, v46, v47
	v_cvt_pk_bf16_f32 v42, v42, v43
	v_cvt_pk_bf16_f32 v43, v52, v53
	global_store_dwordx4 v[44:45], v[40:43], off
	s_cbranch_vccnz .LBB0_552
.LBB0_552:
	s_nop 1
	v_pk_mul_f32 v[36:37], v[36:37], v[236:237] op_sel_hi:[1,0]
	v_pk_mul_f32 v[40:41], v[34:35], v[236:237] op_sel_hi:[1,0]
	v_pk_mul_f32 v[34:35], v[32:33], v[236:237] op_sel_hi:[1,0]
	v_cvt_pk_bf16_f32 v32, v36, v37
	v_mad_i64_i32 v[36:37], s[30:31], v63, v104, 0
	v_pk_mul_f32 v[38:39], v[38:39], v[236:237] op_sel_hi:[1,0]
	v_lshl_add_u64 v[36:37], v[36:37], 1, v[60:61]
	v_cvt_pk_bf16_f32 v33, v38, v39
	v_cvt_pk_bf16_f32 v34, v34, v35
	v_cvt_pk_bf16_f32 v35, v40, v41
	global_store_dwordx4 v[36:37], v[32:35], off
	s_and_b64 vcc, exec, s[2:3]
	s_nop 0
	v_mov_b32_e32 v32, 1.0
	v_mov_b32_e32 v34, 1.0
	s_cbranch_vccnz .LBB0_554
.LBB0_554:
	s_nop 1
	v_pk_mul_f32 v[28:29], v[28:29], v[238:239] op_sel_hi:[1,0]
	v_pk_mul_f32 v[36:37], v[26:27], v[238:239] op_sel_hi:[1,0]
	v_pk_mul_f32 v[26:27], v[24:25], v[238:239] op_sel_hi:[1,0]
	v_cvt_pk_bf16_f32 v24, v28, v29
	v_mad_i64_i32 v[28:29], s[30:31], v63, v96, 0
	v_lshl_add_u64 v[28:29], v[28:29], 1, v[60:61]
	s_and_b64 vcc, exec, s[2:3]
	v_pk_mul_f32 v[30:31], v[30:31], v[238:239] op_sel_hi:[1,0]
	s_nop 0
	v_cvt_pk_bf16_f32 v25, v30, v31
	v_cvt_pk_bf16_f32 v26, v26, v27
	v_cvt_pk_bf16_f32 v27, v36, v37
	global_store_dwordx4 v[28:29], v[24:27], off
	s_cbranch_vccnz .LBB0_556
.LBB0_556:
	s_nop 1
	v_pk_mul_f32 v[20:21], v[20:21], v[240:241] op_sel_hi:[1,0]
	v_pk_mul_f32 v[24:25], v[18:19], v[240:241] op_sel_hi:[1,0]
	v_pk_mul_f32 v[18:19], v[16:17], v[240:241] op_sel_hi:[1,0]
	v_cvt_pk_bf16_f32 v16, v20, v21
	v_mad_i64_i32 v[20:21], s[30:31], v63, v88, 0
	v_pk_mul_f32 v[22:23], v[22:23], v[240:241] op_sel_hi:[1,0]
	v_lshl_add_u64 v[20:21], v[20:21], 1, v[60:61]
	v_cvt_pk_bf16_f32 v17, v22, v23
	v_cvt_pk_bf16_f32 v18, v18, v19
	v_cvt_pk_bf16_f32 v19, v24, v25
	global_store_dwordx4 v[20:21], v[16:19], off
	s_and_b64 vcc, exec, s[2:3]
	s_nop 0
	v_mov_b32_e32 v16, 1.0
	v_mov_b32_e32 v18, 1.0
	s_cbranch_vccnz .LBB0_558
.LBB0_558:
	s_nop 1
	v_pk_mul_f32 v[12:13], v[12:13], v[242:243] op_sel_hi:[1,0]
	v_pk_mul_f32 v[20:21], v[10:11], v[242:243] op_sel_hi:[1,0]
	v_pk_mul_f32 v[10:11], v[8:9], v[242:243] op_sel_hi:[1,0]
	v_cvt_pk_bf16_f32 v8, v12, v13
	v_mad_i64_i32 v[12:13], s[30:31], v63, v80, 0
	v_lshl_add_u64 v[12:13], v[12:13], 1, v[60:61]
	s_and_b64 vcc, exec, s[2:3]
	v_pk_mul_f32 v[14:15], v[14:15], v[242:243] op_sel_hi:[1,0]
	s_nop 0
	v_cvt_pk_bf16_f32 v9, v14, v15
	v_cvt_pk_bf16_f32 v10, v10, v11
	v_cvt_pk_bf16_f32 v11, v20, v21
	global_store_dwordx4 v[12:13], v[8:11], off
	s_cbranch_vccnz .LBB0_560
.LBB0_560:
	s_nop 1
	v_pk_mul_f32 v[4:5], v[4:5], v[244:245] op_sel_hi:[1,0]
	v_pk_mul_f32 v[8:9], v[2:3], v[244:245] op_sel_hi:[1,0]
	v_pk_mul_f32 v[2:3], v[0:1], v[244:245] op_sel_hi:[1,0]
	v_cvt_pk_bf16_f32 v0, v4, v5
	v_mad_i64_i32 v[4:5], s[2:3], v63, v72, 0
	v_lshl_add_u64 v[4:5], v[4:5], 1, v[60:61]
	s_andn2_b64 vcc, exec, s[0:1]
	s_mov_b64 s[0:1], -1
	v_pk_mul_f32 v[6:7], v[6:7], v[244:245] op_sel_hi:[1,0]
	s_nop 0
	v_cvt_pk_bf16_f32 v1, v6, v7
	v_cvt_pk_bf16_f32 v2, v2, v3
	v_cvt_pk_bf16_f32 v3, v8, v9
	global_store_dwordx4 v[4:5], v[0:3], off
	s_cbranch_vccnz .LBB0_521
	s_andn2_b64 vcc, exec, s[10:11]
	s_cbranch_vccnz .LBB0_520
	s_barrier
	s_branch .LBB0_520

; #define PG8_STAGE(bufoff, gbase, voff) do { _Pragma("unroll") for (int _i = 0; _i < 2; ++_i) \
;         __builtin_amdgcn_global_load_lds((const unsigned*)((const char*)(gbase) + (voff)[_i]), (PG8_LAS unsigned*)(lds + (bufoff) + ldsw + _i * 8192), 16, 0, 0); } while (0)
; #define PG8_WAIT_V(n) asm volatile("s_waitcnt vmcnt(" #n ")" ::: "memory")
;     __device__ __forceinline__ void operator()(const f32x4 (&acc)[2][2][4][2], const Unit& u, int wr, int wc, int fr, int fq) const {
;     ...
;                 float h[8]; const float rsc = rs ? rs[row0 + ai * HALF + m * 16] : 1.0f;
; template <class Epi, class Sched, bool ALIGN_EPI = false, bool SP2 = false>
; __device__ __forceinline__ void gemm_phase(PG8_LAS unsigned char* lds, const Gemm g, const Sched& S, const Epi& E) {
;     ...
;     f32x4 acc[2][2][4][2];
; #pragma unroll
;     for (int a = 0; a < 2; ++a)
; #pragma unroll
;         for (int b = 0; b < 2; ++b)
; #pragma unroll
;             for (int m = 0; m < 4; ++m)
; #pragma unroll
;                 for (int n = 0; n < 2; ++n) acc[a][b][m][n] = (f32x4){0.f, 0.f, 0.f, 0.f};
;     bf16x8 At[4][2], B0[2][2], B1[2][2];
;     const char* cA = (const char*)g.A + (size_t)cur.pm * tstep; const char* cB = (const char*)g.Bt + (size_t)cur.pn * tstep;
;     S.a_ready(cur);
;     if constexpr (SP2) {
;         PG8_STAGE(PG8_SB(0, 0), cB, voffB); PG8_STAGE(PG8_SB(0, 1), cB + hstep, voffB); PG8_STAGE(PG8_SA(0, 0), cA, voffA); PG8_STAGE(PG8_SA(0, 1), cA + hstep, voffA);
;         if (wr == 1) PG8_BAR;
;         PG8_WAIT_V(2); PG8_BAR;
;         PG8_STAGE(PG8_SB(1, 0), cB + kstep, voffB); PG8_STAGE(PG8_SA(1, 0), cA + kstep, voffA); PG8_STAGE(PG8_SB(1, 1), cB + hstep + kstep, voffB);
;         PG8_WAIT_V(6); PG8_BAR;
;     } else {
;         PG8_STAGE(PG8_SB(0, 0), cB, voffB); PG8_STAGE(PG8_SA(0, 0), cA, voffA); PG8_STAGE(PG8_SB(0, 1), cB + hstep, voffB); PG8_STAGE(PG8_SA(0, 1), cA + hstep, voffA);
;         if (wr == 1) PG8_BAR;
;         PG8_WAIT_V(4); PG8_BAR;
;         PG8_STAGE(PG8_SB(1, 0), cB + kstep, voffB); PG8_STAGE(PG8_SA(1, 0), cA + kstep, voffA); PG8_STAGE(PG8_SB(1, 1), cB + hstep + kstep, voffB);
;         PG8_WAIT_V(6); PG8_BAR;
;     }
;     for (;;) {
;         const bool has_next = S.next(ui + 1, nxt);
;         const char* nA = has_next ? (const char*)g.A + (size_t)nxt.pm * tstep : cA; const char* nB = has_next ? (const char*)g.Bt + (size_t)nxt.pn * tstep : cB;
.LBB0_1145:
	s_ashr_i32 s19, s18, 31
	s_lshl_b64 s[20:21], s[18:19], 19
	s_add_u32 s20, s80, s20
	s_addc_u32 s21, s81, s21
	s_and_b64 s[22:23], s[0:1], exec
	s_cselect_b32 s3, s21, s27
	s_cselect_b32 s19, s20, s26
	s_ashr_i32 s17, s16, 31
	s_lshl_b64 s[22:23], s[16:17], 19
	s_add_u32 s22, s56, s22
	s_addc_u32 s23, s57, s23
	s_and_b64 s[30:31], s[0:1], exec
	s_cselect_b32 s17, s23, s29
	s_cselect_b32 s47, s22, s28
	s_add_u32 s26, s26, 0x40080
	s_addc_u32 s27, s27, 0
	s_add_u32 s48, s28, 0x100
	v_mov_b32_e32 v0, 0
	s_addc_u32 s49, s29, 0
	s_mov_b32 s50, -2
	v_mov_b32_e32 v1, v0
	v_mov_b32_e32 v2, v0
	v_mov_b32_e32 v3, v0
	v_mov_b32_e32 v8, v0
	v_mov_b32_e32 v9, v0
	v_mov_b32_e32 v10, v0
	v_mov_b32_e32 v11, v0
	v_mov_b32_e32 v16, v0
	v_mov_b32_e32 v17, v0
	v_mov_b32_e32 v18, v0
	v_mov_b32_e32 v19, v0
	v_mov_b32_e32 v24, v0
	v_mov_b32_e32 v25, v0
	v_mov_b32_e32 v26, v0
	v_mov_b32_e32 v27, v0
	v_mov_b32_e32 v32, v0
	v_mov_b32_e32 v33, v0
	v_mov_b32_e32 v34, v0
	v_mov_b32_e32 v35, v0
	v_mov_b32_e32 v40, v0
	v_mov_b32_e32 v41, v0
	v_mov_b32_e32 v42, v0
	v_mov_b32_e32 v43, v0
	v_mov_b32_e32 v48, v0
	v_mov_b32_e32 v49, v0
	v_mov_b32_e32 v50, v0
	v_mov_b32_e32 v51, v0
	v_mov_b32_e32 v56, v0
	v_mov_b32_e32 v57, v0
	v_mov_b32_e32 v58, v0
	v_mov_b32_e32 v59, v0
	v_mov_b32_e32 v4, v0
	v_mov_b32_e32 v5, v0
	v_mov_b32_e32 v6, v0
	v_mov_b32_e32 v7, v0
	v_mov_b32_e32 v12, v0
	v_mov_b32_e32 v13, v0
	v_mov_b32_e32 v14, v0
	v_mov_b32_e32 v15, v0
	v_mov_b32_e32 v20, v0
	v_mov_b32_e32 v21, v0
	v_mov_b32_e32 v22, v0
	v_mov_b32_e32 v23, v0
	v_mov_b32_e32 v28, v0
	v_mov_b32_e32 v29, v0
	v_mov_b32_e32 v30, v0
	v_mov_b32_e32 v31, v0
	v_mov_b32_e32 v36, v0
	v_mov_b32_e32 v37, v0
	v_mov_b32_e32 v38, v0
	v_mov_b32_e32 v39, v0
	v_mov_b32_e32 v44, v0
	v_mov_b32_e32 v45, v0
	v_mov_b32_e32 v46, v0
	v_mov_b32_e32 v47, v0
	v_mov_b32_e32 v52, v0
	v_mov_b32_e32 v53, v0
	v_mov_b32_e32 v54, v0
	v_mov_b32_e32 v55, v0
	v_mov_b32_e32 v60, v0
	v_mov_b32_e32 v61, v0
	v_mov_b32_e32 v62, v0
	v_mov_b32_e32 v63, v0
	v_mov_b32_e32 v64, v0
	v_mov_b32_e32 v65, v0
	v_mov_b32_e32 v66, v0
	v_mov_b32_e32 v67, v0
	v_mov_b32_e32 v72, v0
	v_mov_b32_e32 v73, v0
	v_mov_b32_e32 v74, v0
	v_mov_b32_e32 v75, v0
	v_mov_b32_e32 v80, v0
	v_mov_b32_e32 v81, v0
	v_mov_b32_e32 v82, v0
	v_mov_b32_e32 v83, v0
	v_mov_b32_e32 v88, v0
	v_mov_b32_e32 v89, v0
	v_mov_b32_e32 v90, v0
	v_mov_b32_e32 v91, v0
	v_mov_b32_e32 v96, v0
	v_mov_b32_e32 v97, v0
	v_mov_b32_e32 v98, v0
	v_mov_b32_e32 v99, v0
	v_mov_b32_e32 v104, v0
	v_mov_b32_e32 v105, v0
	v_mov_b32_e32 v106, v0
	v_mov_b32_e32 v107, v0
	v_mov_b32_e32 v112, v0
	v_mov_b32_e32 v113, v0
	v_mov_b32_e32 v114, v0
	v_mov_b32_e32 v115, v0
	v_mov_b32_e32 v120, v0
	v_mov_b32_e32 v121, v0
	v_mov_b32_e32 v122, v0
	v_mov_b32_e32 v123, v0
	v_mov_b32_e32 v68, v0
	v_mov_b32_e32 v69, v0
	v_mov_b32_e32 v70, v0
	v_mov_b32_e32 v71, v0
	v_mov_b32_e32 v76, v0
	v_mov_b32_e32 v77, v0
	v_mov_b32_e32 v78, v0
	v_mov_b32_e32 v79, v0
	v_mov_b32_e32 v84, v0
	v_mov_b32_e32 v85, v0
	v_mov_b32_e32 v86, v0
	v_mov_b32_e32 v87, v0
	v_mov_b32_e32 v92, v0
	v_mov_b32_e32 v93, v0
	v_mov_b32_e32 v94, v0
	v_mov_b32_e32 v95, v0
	v_mov_b32_e32 v100, v0
	v_mov_b32_e32 v101, v0
	v_mov_b32_e32 v102, v0
	v_mov_b32_e32 v103, v0
	v_mov_b32_e32 v108, v0
	v_mov_b32_e32 v109, v0
	v_mov_b32_e32 v110, v0
	v_mov_b32_e32 v111, v0
	v_mov_b32_e32 v116, v0
	v_mov_b32_e32 v117, v0
	v_mov_b32_e32 v118, v0
	v_mov_b32_e32 v119, v0
	v_mov_b32_e32 v124, v0
	v_mov_b32_e32 v125, v0
	v_mov_b32_e32 v126, v0
	v_mov_b32_e32 v127, v0
	v_lshl_add_u32 v146, s2, 8, v149
	v_ashrrev_i32_e32 v147, 31, v146
	v_lshl_add_u64 v[144:145], v[146:147], 2, s[4:5]
	global_load_dword v230, v[144:145], off
	global_load_dword v232, v[144:145], off offset:64
	global_load_dword v234, v[144:145], off offset:128
	global_load_dword v236, v[144:145], off offset:192
	global_load_dword v238, v[144:145], off offset:512
	global_load_dword v240, v[144:145], off offset:576
	global_load_dword v242, v[144:145], off offset:640
	global_load_dword v244, v[144:145], off offset:704

; __device__ __forceinline__ unsigned cvt_pk_bf16(float lo, float hi) { unsigned r; asm volatile("v_cvt_pk_bf16_f32 %0, %1, %2" : "=v"(r) : "v"(lo), "v"(hi)); return r; }
;     __device__ __forceinline__ void operator()(const f32x4 (&acc)[2][2][4][2], const Unit& u, int wr, int wc, int fr, int fq) const {
;         const int row0 = u.pm * BM + wr * 64 + fr, col0 = u.pn * 128 + wc * 32 + 8 * fq;
; #pragma unroll
;         for (int ai = 0; ai < 2; ++ai)
; #pragma unroll
;             for (int m = 0; m < 4; ++m) {
;                 bf16_t* p = O + (size_t)(row0 + ai * HALF + m * 16) * ldc + col0;
;                 float h[8]; const float rsc = rs ? rs[row0 + ai * HALF + m * 16] : 1.0f;
; #pragma unroll
;                 for (int n = 0; n < 2; ++n)
; #pragma unroll
;                     for (int i = 0; i < 4; ++i) { const float g = acc[ai][0][m][n][i] * rsc, uu = acc[ai][1][m][n][i] * rsc; h[4 * n + i] = g * __builtin_amdgcn_rcpf(1.0f + __builtin_amdgcn_exp2f(g)) * uu; }
;                 u32x4 w; w.x = cvt_pk_bf16(h[0], h[1]); w.y = cvt_pk_bf16(h[2], h[3]); w.z = cvt_pk_bf16(h[4], h[5]); w.w = cvt_pk_bf16(h[6], h[7]);
;                 *(u32x4*)p = w;
;             }
.LBB0_1149:
	s_mov_b32 s98, 0x16000
	s_mov_b32 s99, 0
	s_mov_b32 s100, 0x6e000
	s_mov_b32 s101, 0
	v_lshl_add_u32 v146, s2, 8, v149
	v_ashrrev_i32_e32 v147, 31, v146
	v_mov_b64_e32 v[156:157], s[76:77]
	v_mov_b32_e32 v176, 1.0
	v_mad_i64_i32 v[198:199], s[26:27], v146, s46, v[156:157]
	v_lshl_or_b32 v144, s24, 7, v152
	v_ashrrev_i32_e32 v145, 31, v144
	v_lshl_add_u64 v[198:199], v[144:145], 1, v[198:199]
	v_lshl_add_u64 v[200:201], v[198:199], 0, s[98:99]
	v_lshl_add_u64 v[202:203], v[200:201], 0, s[98:99]
	v_lshl_add_u64 v[204:205], v[202:203], 0, s[98:99]
	v_lshl_add_u64 v[206:207], v[204:205], 0, s[100:101]
	v_lshl_add_u64 v[208:209], v[206:207], 0, s[98:99]
	v_lshl_add_u64 v[210:211], v[208:209], 0, s[98:99]
	v_lshl_add_u64 v[212:213], v[210:211], 0, s[98:99]
	v_pk_mul_f32 v[124:125], v[124:125], v[230:231] op_sel_hi:[1,0]
	v_pk_mul_f32 v[126:127], v[126:127], v[230:231] op_sel_hi:[1,0]
	v_pk_mul_f32 v[116:117], v[116:117], v[230:231] op_sel_hi:[1,0]
	v_pk_mul_f32 v[118:119], v[118:119], v[230:231] op_sel_hi:[1,0]
	v_pk_mul_f32 v[120:121], v[120:121], v[230:231] op_sel_hi:[1,0]
	v_pk_mul_f32 v[122:123], v[122:123], v[230:231] op_sel_hi:[1,0]
	v_pk_mul_f32 v[112:113], v[112:113], v[230:231] op_sel_hi:[1,0]
	v_pk_mul_f32 v[114:115], v[114:115], v[230:231] op_sel_hi:[1,0]
	v_pk_mul_f32 v[108:109], v[108:109], v[232:233] op_sel_hi:[1,0]
	v_pk_mul_f32 v[110:111], v[110:111], v[232:233] op_sel_hi:[1,0]
	v_pk_mul_f32 v[100:101], v[100:101], v[232:233] op_sel_hi:[1,0]
	v_pk_mul_f32 v[102:103], v[102:103], v[232:233] op_sel_hi:[1,0]
	v_pk_mul_f32 v[104:105], v[104:105], v[232:233] op_sel_hi:[1,0]
	v_pk_mul_f32 v[106:107], v[106:107], v[232:233] op_sel_hi:[1,0]
	v_pk_mul_f32 v[96:97], v[96:97], v[232:233] op_sel_hi:[1,0]
	v_pk_mul_f32 v[98:99], v[98:99], v[232:233] op_sel_hi:[1,0]
	v_exp_f32_e32 v160, v124
	v_pk_mul_f32 v[92:93], v[92:93], v[234:235] op_sel_hi:[1,0]
	v_exp_f32_e32 v161, v125
	v_pk_mul_f32 v[94:95], v[94:95], v[234:235] op_sel_hi:[1,0]
	v_exp_f32_e32 v162, v126
	v_pk_mul_f32 v[84:85], v[84:85], v[234:235] op_sel_hi:[1,0]
	v_exp_f32_e32 v163, v127
	v_pk_mul_f32 v[86:87], v[86:87], v[234:235] op_sel_hi:[1,0]
	v_exp_f32_e32 v164, v116
	v_pk_mul_f32 v[88:89], v[88:89], v[234:235] op_sel_hi:[1,0]
	v_exp_f32_e32 v165, v117
	v_pk_mul_f32 v[90:91], v[90:91], v[234:235] op_sel_hi:[1,0]
	v_exp_f32_e32 v166, v118
	v_pk_mul_f32 v[80:81], v[80:81], v[234:235] op_sel_hi:[1,0]
	v_exp_f32_e32 v167, v119
	v_pk_mul_f32 v[82:83], v[82:83], v[234:235] op_sel_hi:[1,0]
	v_exp_f32_e32 v168, v108
	v_pk_mul_f32 v[76:77], v[76:77], v[236:237] op_sel_hi:[1,0]
	v_exp_f32_e32 v169, v109
	v_pk_mul_f32 v[78:79], v[78:79], v[236:237] op_sel_hi:[1,0]
	v_exp_f32_e32 v170, v110
	v_pk_mul_f32 v[68:69], v[68:69], v[236:237] op_sel_hi:[1,0]
	v_exp_f32_e32 v171, v111
	v_pk_mul_f32 v[70:71], v[70:71], v[236:237] op_sel_hi:[1,0]
	v_exp_f32_e32 v172, v100
	v_pk_mul_f32 v[72:73], v[72:73], v[236:237] op_sel_hi:[1,0]
	v_exp_f32_e32 v173, v101
	v_pk_mul_f32 v[74:75], v[74:75], v[236:237] op_sel_hi:[1,0]
	v_exp_f32_e32 v174, v102
	v_pk_mul_f32 v[64:65], v[64:65], v[236:237] op_sel_hi:[1,0]
	v_exp_f32_e32 v175, v103
	v_pk_mul_f32 v[66:67], v[66:67], v[236:237] op_sel_hi:[1,0]
	v_pk_add_f32 v[160:161], v[160:161], v[176:177] op_sel_hi:[1,0]
	v_pk_add_f32 v[162:163], v[162:163], v[176:177] op_sel_hi:[1,0]
	v_pk_add_f32 v[164:165], v[164:165], v[176:177] op_sel_hi:[1,0]
	v_pk_add_f32 v[166:167], v[166:167], v[176:177] op_sel_hi:[1,0]
	v_pk_add_f32 v[168:169], v[168:169], v[176:177] op_sel_hi:[1,0]
	v_pk_add_f32 v[170:171], v[170:171], v[176:177] op_sel_hi:[1,0]
	v_pk_add_f32 v[172:173], v[172:173], v[176:177] op_sel_hi:[1,0]
	v_pk_add_f32 v[174:175], v[174:175], v[176:177] op_sel_hi:[1,0]
	v_rcp_f32_e32 v160, v160
	v_rcp_f32_e32 v161, v161
	v_rcp_f32_e32 v162, v162
	v_rcp_f32_e32 v163, v163
	v_rcp_f32_e32 v164, v164
	v_rcp_f32_e32 v165, v165
	v_rcp_f32_e32 v166, v166
	v_rcp_f32_e32 v167, v167
	v_rcp_f32_e32 v168, v168
	v_rcp_f32_e32 v169, v169
	v_rcp_f32_e32 v170, v170
	v_rcp_f32_e32 v171, v171
	v_rcp_f32_e32 v172, v172
	v_rcp_f32_e32 v173, v173
	v_rcp_f32_e32 v174, v174
	v_rcp_f32_e32 v175, v175
	v_pk_mul_f32 v[124:125], v[124:125], v[160:161]
	v_exp_f32_e32 v160, v92
	v_pk_mul_f32 v[126:127], v[126:127], v[162:163]
	v_exp_f32_e32 v161, v93
	v_pk_mul_f32 v[116:117], v[116:117], v[164:165]
	v_exp_f32_e32 v162, v94
	v_pk_mul_f32 v[118:119], v[118:119], v[166:167]
	v_exp_f32_e32 v163, v95
	v_pk_mul_f32 v[108:109], v[108:109], v[168:169]
	v_exp_f32_e32 v164, v84
	v_pk_mul_f32 v[110:111], v[110:111], v[170:171]
	v_exp_f32_e32 v165, v85
	v_pk_mul_f32 v[100:101], v[100:101], v[172:173]
	v_exp_f32_e32 v166, v86
	v_pk_mul_f32 v[102:103], v[102:103], v[174:175]
	v_exp_f32_e32 v167, v87
	v_pk_mul_f32 v[120:121], v[124:125], v[120:121]
	v_exp_f32_e32 v168, v76
	v_pk_mul_f32 v[122:123], v[126:127], v[122:123]
	v_exp_f32_e32 v169, v77
	v_pk_mul_f32 v[112:113], v[116:117], v[112:113]
	v_exp_f32_e32 v170, v78
	v_pk_mul_f32 v[114:115], v[118:119], v[114:115]
	v_exp_f32_e32 v171, v79
	v_pk_mul_f32 v[104:105], v[108:109], v[104:105]
	v_exp_f32_e32 v172, v68
	v_pk_mul_f32 v[106:107], v[110:111], v[106:107]
	v_exp_f32_e32 v173, v69
	v_pk_mul_f32 v[96:97], v[100:101], v[96:97]
	v_exp_f32_e32 v174, v70
	v_pk_mul_f32 v[98:99], v[102:103], v[98:99]
	v_exp_f32_e32 v175, v71
	v_pk_add_f32 v[160:161], v[160:161], v[176:177] op_sel_hi:[1,0]
	v_pk_add_f32 v[162:163], v[162:163], v[176:177] op_sel_hi:[1,0]
	v_pk_add_f32 v[164:165], v[164:165], v[176:177] op_sel_hi:[1,0]
	v_pk_add_f32 v[166:167], v[166:167], v[176:177] op_sel_hi:[1,0]
	v_pk_add_f32 v[168:169], v[168:169], v[176:177] op_sel_hi:[1,0]
; __device__ __forceinline__ unsigned cvt_pk_bf16(float lo, float hi) { unsigned r; asm volatile("v_cvt_pk_bf16_f32 %0, %1, %2" : "=v"(r) : "v"(lo), "v"(hi)); return r; }
;     __device__ __forceinline__ void operator()(const f32x4 (&acc)[2][2][4][2], const Unit& u, int wr, int wc, int fr, int fq) const {
;     ...
;             for (int m = 0; m < 4; ++m) {
;                 bf16_t* p = O + (size_t)(row0 + ai * HALF + m * 16) * ldc + col0;
;                 float h[8]; const float rsc = rs ? rs[row0 + ai * HALF + m * 16] : 1.0f;
; #pragma unroll
;                 for (int n = 0; n < 2; ++n)
; #pragma unroll
;                     for (int i = 0; i < 4; ++i) { const float g = acc[ai][0][m][n][i] * rsc, uu = acc[ai][1][m][n][i] * rsc; h[4 * n + i] = g * __builtin_amdgcn_rcpf(1.0f + __builtin_amdgcn_exp2f(g)) * uu; }
;                 u32x4 w; w.x = cvt_pk_bf16(h[0], h[1]); w.y = cvt_pk_bf16(h[2], h[3]); w.z = cvt_pk_bf16(h[4], h[5]); w.w = cvt_pk_bf16(h[6], h[7]);
;                 *(u32x4*)p = w;
	v_pk_add_f32 v[170:171], v[170:171], v[176:177] op_sel_hi:[1,0]
	v_pk_add_f32 v[172:173], v[172:173], v[176:177] op_sel_hi:[1,0]
	v_pk_add_f32 v[174:175], v[174:175], v[176:177] op_sel_hi:[1,0]
	v_rcp_f32_e32 v160, v160
	v_cvt_pk_bf16_f32 v116, v120, v121
	v_rcp_f32_e32 v161, v161
	v_cvt_pk_bf16_f32 v117, v122, v123
	v_rcp_f32_e32 v162, v162
	v_cvt_pk_bf16_f32 v118, v112, v113
	v_rcp_f32_e32 v163, v163
	v_cvt_pk_bf16_f32 v119, v114, v115
	v_rcp_f32_e32 v164, v164
	v_cvt_pk_bf16_f32 v100, v104, v105
	v_rcp_f32_e32 v165, v165
	v_cvt_pk_bf16_f32 v101, v106, v107
	v_rcp_f32_e32 v166, v166
	v_cvt_pk_bf16_f32 v102, v96, v97
	v_rcp_f32_e32 v167, v167
	v_cvt_pk_bf16_f32 v103, v98, v99
	v_rcp_f32_e32 v168, v168
	global_store_dwordx4 v[198:199], v[116:119], off
	v_rcp_f32_e32 v169, v169
	global_store_dwordx4 v[200:201], v[100:103], off
	v_rcp_f32_e32 v170, v170
	v_pk_mul_f32 v[60:61], v[60:61], v[238:239] op_sel_hi:[1,0]
	v_rcp_f32_e32 v171, v171
	v_pk_mul_f32 v[62:63], v[62:63], v[238:239] op_sel_hi:[1,0]
	v_rcp_f32_e32 v172, v172
	v_pk_mul_f32 v[52:53], v[52:53], v[238:239] op_sel_hi:[1,0]
	v_rcp_f32_e32 v173, v173
	v_pk_mul_f32 v[54:55], v[54:55], v[238:239] op_sel_hi:[1,0]
	v_rcp_f32_e32 v174, v174
	v_pk_mul_f32 v[56:57], v[56:57], v[238:239] op_sel_hi:[1,0]
	v_rcp_f32_e32 v175, v175
	v_pk_mul_f32 v[58:59], v[58:59], v[238:239] op_sel_hi:[1,0]
	v_pk_mul_f32 v[48:49], v[48:49], v[238:239] op_sel_hi:[1,0]
	v_pk_mul_f32 v[50:51], v[50:51], v[238:239] op_sel_hi:[1,0]
	v_pk_mul_f32 v[44:45], v[44:45], v[240:241] op_sel_hi:[1,0]
	v_pk_mul_f32 v[46:47], v[46:47], v[240:241] op_sel_hi:[1,0]
	v_pk_mul_f32 v[36:37], v[36:37], v[240:241] op_sel_hi:[1,0]
	v_pk_mul_f32 v[38:39], v[38:39], v[240:241] op_sel_hi:[1,0]
	v_pk_mul_f32 v[40:41], v[40:41], v[240:241] op_sel_hi:[1,0]
	v_pk_mul_f32 v[42:43], v[42:43], v[240:241] op_sel_hi:[1,0]
	v_pk_mul_f32 v[32:33], v[32:33], v[240:241] op_sel_hi:[1,0]
	v_pk_mul_f32 v[34:35], v[34:35], v[240:241] op_sel_hi:[1,0]
	v_pk_mul_f32 v[92:93], v[92:93], v[160:161]
	v_exp_f32_e32 v160, v60
	v_pk_mul_f32 v[94:95], v[94:95], v[162:163]
	v_exp_f32_e32 v161, v61
	v_pk_mul_f32 v[84:85], v[84:85], v[164:165]
	v_exp_f32_e32 v162, v62
	v_pk_mul_f32 v[86:87], v[86:87], v[166:167]
	v_exp_f32_e32 v163, v63
	v_pk_mul_f32 v[76:77], v[76:77], v[168:169]
	v_exp_f32_e32 v164, v52
	v_pk_mul_f32 v[78:79], v[78:79], v[170:171]
	v_exp_f32_e32 v165, v53
	v_pk_mul_f32 v[68:69], v[68:69], v[172:173]
	v_exp_f32_e32 v166, v54
	v_pk_mul_f32 v[70:71], v[70:71], v[174:175]
	v_exp_f32_e32 v167, v55
	v_pk_mul_f32 v[88:89], v[92:93], v[88:89]
	v_exp_f32_e32 v168, v44
	v_pk_mul_f32 v[90:91], v[94:95], v[90:91]
	v_exp_f32_e32 v169, v45
	v_pk_mul_f32 v[80:81], v[84:85], v[80:81]
	v_exp_f32_e32 v170, v46
	v_pk_mul_f32 v[82:83], v[86:87], v[82:83]
	v_exp_f32_e32 v171, v47
	v_pk_mul_f32 v[72:73], v[76:77], v[72:73]
	v_exp_f32_e32 v172, v36
	v_pk_mul_f32 v[74:75], v[78:79], v[74:75]
	v_exp_f32_e32 v173, v37
	v_pk_mul_f32 v[64:65], v[68:69], v[64:65]
	v_exp_f32_e32 v174, v38
	v_pk_mul_f32 v[66:67], v[70:71], v[66:67]
	v_exp_f32_e32 v175, v39
	v_pk_add_f32 v[160:161], v[160:161], v[176:177] op_sel_hi:[1,0]
	v_pk_add_f32 v[162:163], v[162:163], v[176:177] op_sel_hi:[1,0]
	v_pk_add_f32 v[164:165], v[164:165], v[176:177] op_sel_hi:[1,0]
	v_pk_add_f32 v[166:167], v[166:167], v[176:177] op_sel_hi:[1,0]
	v_pk_add_f32 v[168:169], v[168:169], v[176:177] op_sel_hi:[1,0]
	v_pk_add_f32 v[170:171], v[170:171], v[176:177] op_sel_hi:[1,0]
	v_pk_add_f32 v[172:173], v[172:173], v[176:177] op_sel_hi:[1,0]
	v_pk_add_f32 v[174:175], v[174:175], v[176:177] op_sel_hi:[1,0]
	v_rcp_f32_e32 v160, v160
	v_cvt_pk_bf16_f32 v84, v88, v89
	v_rcp_f32_e32 v161, v161
	v_cvt_pk_bf16_f32 v85, v90, v91
	v_rcp_f32_e32 v162, v162
	v_cvt_pk_bf16_f32 v86, v80, v81
	v_rcp_f32_e32 v163, v163
	v_cvt_pk_bf16_f32 v87, v82, v83
	v_rcp_f32_e32 v164, v164
	v_cvt_pk_bf16_f32 v68, v72, v73
	v_rcp_f32_e32 v165, v165
	v_cvt_pk_bf16_f32 v69, v74, v75
	v_rcp_f32_e32 v166, v166
	v_cvt_pk_bf16_f32 v70, v64, v65
	v_rcp_f32_e32 v167, v167
	v_cvt_pk_bf16_f32 v71, v66, v67
	v_rcp_f32_e32 v168, v168
	global_store_dwordx4 v[202:203], v[84:87], off
	v_rcp_f32_e32 v169, v169
	global_store_dwordx4 v[204:205], v[68:71], off
	v_rcp_f32_e32 v170, v170
	v_pk_mul_f32 v[28:29], v[28:29], v[242:243] op_sel_hi:[1,0]
	v_rcp_f32_e32 v171, v171
	v_pk_mul_f32 v[30:31], v[30:31], v[242:243] op_sel_hi:[1,0]
	v_rcp_f32_e32 v172, v172
	v_pk_mul_f32 v[20:21], v[20:21], v[242:243] op_sel_hi:[1,0]
; __device__ __forceinline__ unsigned cvt_pk_bf16(float lo, float hi) { unsigned r; asm volatile("v_cvt_pk_bf16_f32 %0, %1, %2" : "=v"(r) : "v"(lo), "v"(hi)); return r; }
; #define PG8_BAR __builtin_amdgcn_s_barrier()
;     __device__ __forceinline__ void operator()(const f32x4 (&acc)[2][2][4][2], const Unit& u, int wr, int wc, int fr, int fq) const {
;     ...
;             for (int m = 0; m < 4; ++m) {
;                 bf16_t* p = O + (size_t)(row0 + ai * HALF + m * 16) * ldc + col0;
;                 float h[8]; const float rsc = rs ? rs[row0 + ai * HALF + m * 16] : 1.0f;
; #pragma unroll
;                 for (int n = 0; n < 2; ++n)
; #pragma unroll
;                     for (int i = 0; i < 4; ++i) { const float g = acc[ai][0][m][n][i] * rsc, uu = acc[ai][1][m][n][i] * rsc; h[4 * n + i] = g * __builtin_amdgcn_rcpf(1.0f + __builtin_amdgcn_exp2f(g)) * uu; }
;                 u32x4 w; w.x = cvt_pk_bf16(h[0], h[1]); w.y = cvt_pk_bf16(h[2], h[3]); w.z = cvt_pk_bf16(h[4], h[5]); w.w = cvt_pk_bf16(h[6], h[7]);
;                 *(u32x4*)p = w;
; template <class Epi, class Sched, bool ALIGN_EPI = false, bool SP2 = false>
; __device__ __forceinline__ void gemm_phase(PG8_LAS unsigned char* lds, const Gemm g, const Sched& S, const Epi& E) {
;     ...
;         if (!has_next) break;
; #pragma unroll
;         for (int a = 0; a < 2; ++a)
; #pragma unroll
;             for (int b = 0; b < 2; ++b)
; #pragma unroll
;                 for (int m = 0; m < 4; ++m)
; #pragma unroll
;                     for (int n = 0; n < 2; ++n) acc[a][b][m][n] = (f32x4){0.f, 0.f, 0.f, 0.f};
;         cur = nxt; cA = nA; cB = nB; ++ui;
;         if constexpr (ALIGN_EPI) { if (wr == 1) PG8_BAR; }
	v_rcp_f32_e32 v173, v173
	v_pk_mul_f32 v[22:23], v[22:23], v[242:243] op_sel_hi:[1,0]
	v_rcp_f32_e32 v174, v174
	v_pk_mul_f32 v[24:25], v[24:25], v[242:243] op_sel_hi:[1,0]
	v_rcp_f32_e32 v175, v175
	v_pk_mul_f32 v[26:27], v[26:27], v[242:243] op_sel_hi:[1,0]
	v_pk_mul_f32 v[16:17], v[16:17], v[242:243] op_sel_hi:[1,0]
	v_pk_mul_f32 v[18:19], v[18:19], v[242:243] op_sel_hi:[1,0]
	v_pk_mul_f32 v[12:13], v[12:13], v[244:245] op_sel_hi:[1,0]
	v_pk_mul_f32 v[14:15], v[14:15], v[244:245] op_sel_hi:[1,0]
	v_pk_mul_f32 v[4:5], v[4:5], v[244:245] op_sel_hi:[1,0]
	v_pk_mul_f32 v[6:7], v[6:7], v[244:245] op_sel_hi:[1,0]
	v_pk_mul_f32 v[8:9], v[8:9], v[244:245] op_sel_hi:[1,0]
	v_pk_mul_f32 v[10:11], v[10:11], v[244:245] op_sel_hi:[1,0]
	v_pk_mul_f32 v[0:1], v[0:1], v[244:245] op_sel_hi:[1,0]
	v_pk_mul_f32 v[2:3], v[2:3], v[244:245] op_sel_hi:[1,0]
	v_pk_mul_f32 v[60:61], v[60:61], v[160:161]
	v_exp_f32_e32 v160, v28
	v_pk_mul_f32 v[62:63], v[62:63], v[162:163]
	v_exp_f32_e32 v161, v29
	v_pk_mul_f32 v[52:53], v[52:53], v[164:165]
	v_exp_f32_e32 v162, v30
	v_pk_mul_f32 v[54:55], v[54:55], v[166:167]
	v_exp_f32_e32 v163, v31
	v_pk_mul_f32 v[44:45], v[44:45], v[168:169]
	v_exp_f32_e32 v164, v20
	v_pk_mul_f32 v[46:47], v[46:47], v[170:171]
	v_exp_f32_e32 v165, v21
	v_pk_mul_f32 v[36:37], v[36:37], v[172:173]
	v_exp_f32_e32 v166, v22
	v_pk_mul_f32 v[38:39], v[38:39], v[174:175]
	v_exp_f32_e32 v167, v23
	v_pk_mul_f32 v[56:57], v[60:61], v[56:57]
	v_exp_f32_e32 v168, v12
	v_pk_mul_f32 v[58:59], v[62:63], v[58:59]
	v_exp_f32_e32 v169, v13
	v_pk_mul_f32 v[48:49], v[52:53], v[48:49]
	v_exp_f32_e32 v170, v14
	v_pk_mul_f32 v[50:51], v[54:55], v[50:51]
	v_exp_f32_e32 v171, v15
	v_pk_mul_f32 v[40:41], v[44:45], v[40:41]
	v_exp_f32_e32 v172, v4
	v_pk_mul_f32 v[42:43], v[46:47], v[42:43]
	v_exp_f32_e32 v173, v5
	v_pk_mul_f32 v[32:33], v[36:37], v[32:33]
	v_exp_f32_e32 v174, v6
	v_pk_mul_f32 v[34:35], v[38:39], v[34:35]
	v_exp_f32_e32 v175, v7
	v_pk_add_f32 v[160:161], v[160:161], v[176:177] op_sel_hi:[1,0]
	v_pk_add_f32 v[162:163], v[162:163], v[176:177] op_sel_hi:[1,0]
	v_pk_add_f32 v[164:165], v[164:165], v[176:177] op_sel_hi:[1,0]
	v_pk_add_f32 v[166:167], v[166:167], v[176:177] op_sel_hi:[1,0]
	v_pk_add_f32 v[168:169], v[168:169], v[176:177] op_sel_hi:[1,0]
	v_pk_add_f32 v[170:171], v[170:171], v[176:177] op_sel_hi:[1,0]
	v_pk_add_f32 v[172:173], v[172:173], v[176:177] op_sel_hi:[1,0]
	v_pk_add_f32 v[174:175], v[174:175], v[176:177] op_sel_hi:[1,0]
	v_rcp_f32_e32 v160, v160
	v_cvt_pk_bf16_f32 v52, v56, v57
	v_rcp_f32_e32 v161, v161
	v_cvt_pk_bf16_f32 v53, v58, v59
	v_rcp_f32_e32 v162, v162
	v_cvt_pk_bf16_f32 v54, v48, v49
	v_rcp_f32_e32 v163, v163
	v_cvt_pk_bf16_f32 v55, v50, v51
	v_rcp_f32_e32 v164, v164
	v_cvt_pk_bf16_f32 v36, v40, v41
	v_rcp_f32_e32 v165, v165
	v_cvt_pk_bf16_f32 v37, v42, v43
	v_rcp_f32_e32 v166, v166
	v_cvt_pk_bf16_f32 v38, v32, v33
	v_rcp_f32_e32 v167, v167
	v_cvt_pk_bf16_f32 v39, v34, v35
	v_rcp_f32_e32 v168, v168
	global_store_dwordx4 v[206:207], v[52:55], off
	v_rcp_f32_e32 v169, v169
	global_store_dwordx4 v[208:209], v[36:39], off
	v_rcp_f32_e32 v170, v170
	v_rcp_f32_e32 v171, v171
	v_rcp_f32_e32 v172, v172
	v_rcp_f32_e32 v173, v173
	v_rcp_f32_e32 v174, v174
	v_rcp_f32_e32 v175, v175
	v_pk_mul_f32 v[28:29], v[28:29], v[160:161]
	v_pk_mul_f32 v[30:31], v[30:31], v[162:163]
	v_pk_mul_f32 v[20:21], v[20:21], v[164:165]
	v_pk_mul_f32 v[22:23], v[22:23], v[166:167]
	v_pk_mul_f32 v[12:13], v[12:13], v[168:169]
	v_pk_mul_f32 v[14:15], v[14:15], v[170:171]
	v_pk_mul_f32 v[4:5], v[4:5], v[172:173]
	v_pk_mul_f32 v[6:7], v[6:7], v[174:175]
	v_pk_mul_f32 v[24:25], v[28:29], v[24:25]
	v_pk_mul_f32 v[26:27], v[30:31], v[26:27]
	v_pk_mul_f32 v[16:17], v[20:21], v[16:17]
	v_pk_mul_f32 v[18:19], v[22:23], v[18:19]
	v_pk_mul_f32 v[8:9], v[12:13], v[8:9]
	v_pk_mul_f32 v[10:11], v[14:15], v[10:11]
	v_pk_mul_f32 v[0:1], v[4:5], v[0:1]
	v_pk_mul_f32 v[2:3], v[6:7], v[2:3]
	v_cvt_pk_bf16_f32 v20, v24, v25
	v_cvt_pk_bf16_f32 v21, v26, v27
	v_cvt_pk_bf16_f32 v22, v16, v17
	v_cvt_pk_bf16_f32 v23, v18, v19
	v_cvt_pk_bf16_f32 v4, v8, v9
	v_cvt_pk_bf16_f32 v5, v10, v11
	v_cvt_pk_bf16_f32 v6, v0, v1
	v_cvt_pk_bf16_f32 v7, v2, v3
	global_store_dwordx4 v[210:211], v[20:23], off
	global_store_dwordx4 v[212:213], v[4:7], off
	s_andn2_b64 vcc, exec, s[0:1]
	s_mov_b64 s[0:1], -1
	s_cbranch_vccnz .LBB0_1142
	s_andn2_b64 vcc, exec, s[8:9]
	s_cbranch_vccnz .LBB0_1141
	s_barrier
	s_branch .LBB0_1141
